# fcum q/k bound loop: next iteration's 16 row loads prefetched into spare VGPRs at the top of each iteration (one vmcnt(0) per iteration)
# speedup vs baseline: 1.0013x; 1.0013x over previous
; __device__ __forceinline__ void p5a_fcum(const Args& A, char* lds, int G) {
;     ...
;         for (int i = 0; i < 4; ++i) { const float f2v = (off + v[i]) * LOG2E; const int t = 4 * tid + i; F2[(size_t)item * SEQL + t] = f2v;
;             if ((t & 127) == 127) wtot[64 + (t >> 7)] = f2v; if ((t & 255) == 0) wtot[96 + (t >> 8)] = f2v; }
;         { const bf16* P1 = (const bf16*)(A.ws + WS_BIG); float qm = 0.f, km = 0.f;
; #pragma unroll 8
;           for (int i = 0; i < 32; ++i) { const size_t m = (size_t)b * SEQL + (tid >> 3) + 64 * i; const int c8 = tid & 7; float qs = 0.f, ks2 = 0.f;
;               const bf16x8 qv = *(const bf16x8*)(P1 + m * LD1 + C1_Q + h * 64 + c8 * 8), kv = *(const bf16x8*)(P1 + m * LD1 + C1_K + h * 64 + c8 * 8);
.LBB0_1330:
	s_or_b64 exec, exec, s[56:57]
	v_sub_f32_e32 v11, 0, v39
	s_ashr_i32 s53, s52, 31
	s_lshl_b64 s[56:57], s[52:53], 13
	v_add_f32_e32 v11, v11, v2
	v_mul_f32_e32 v11, 0x3fb8aa3b, v11
	v_lshl_add_u64 v[14:15], v[6:7], 0, s[56:57]
	flat_store_dword v[14:15], v11
	s_and_saveexec_b64 s[56:57], s[10:11]
	ds_write_b32 v17, v11 offset:384
	s_or_b64 exec, exec, s[56:57]
	v_pk_add_f32 v[0:1], v[0:1], v[2:3] op_sel_hi:[1,0]
	v_add_f32_e32 v2, v3, v2
	v_pk_mul_f32 v[0:1], v[0:1], s[50:51] op_sel_hi:[1,0]
	v_mul_f32_e32 v2, 0x3fb8aa3b, v2
	flat_store_dwordx3 v[14:15], v[0:2] offset:4
	s_and_saveexec_b64 s[56:57], s[24:25]
	ds_write_b32 v18, v2 offset:256
	s_or_b64 exec, exec, s[56:57]
	s_lshl_b32 s54, s54, 6
	s_ashr_i32 s55, s54, 31
	s_mul_hi_i32 s53, s30, 0x1c00000
	s_mul_i32 s56, s30, 0x1c00000
	s_lshl_b64 s[30:31], s[54:55], 1
	s_add_u32 s30, s56, s30
	s_addc_u32 s31, s53, s31
	v_lshl_add_u64 v[0:1], v[8:9], 0, s[30:31]
	v_mov_b32_e32 v11, 0
	s_mov_b64 s[54:55], 0
	v_mov_b32_e32 v14, 0
	v_lshl_add_u64 v[2:3], v[0:1], 0, s[54:55]
	v_add_co_u32_e64 v168, s[30:31], s65, v2
	v_add_co_u32_e32 v20, vcc, 0x1b00000, v2
	s_nop 0
	v_addc_co_u32_e64 v169, s[30:31], 0, v3, s[30:31]
	v_add_co_u32_e64 v172, s[30:31], s66, v2
	v_addc_co_u32_e32 v21, vcc, 0, v3, vcc
	s_nop 0
	v_addc_co_u32_e64 v173, s[30:31], 0, v3, s[30:31]
	v_add_co_u32_e64 v176, s[30:31], s67, v2
	s_add_u32 s54, s54, 0x700000
	s_nop 0
	v_addc_co_u32_e64 v177, s[30:31], 0, v3, s[30:31]
	v_add_co_u32_e64 v180, s[30:31], s68, v2
	s_addc_u32 s55, s55, 0
	s_nop 0
	v_addc_co_u32_e64 v181, s[30:31], 0, v3, s[30:31]
	v_add_co_u32_e64 v184, s[30:31], s69, v2
	s_nop 0
	s_nop 0
	v_addc_co_u32_e64 v185, s[30:31], 0, v3, s[30:31]
	v_add_co_u32_e64 v188, s[30:31], s71, v2
	s_nop 1
	v_addc_co_u32_e64 v189, s[30:31], 0, v3, s[30:31]
	v_add_co_u32_e64 v192, s[30:31], s72, v2
	s_nop 1
	v_addc_co_u32_e64 v193, s[30:31], 0, v3, s[30:31]
	v_add_co_u32_e64 v196, s[30:31], s73, v2
	s_nop 1
	v_addc_co_u32_e64 v197, s[30:31], 0, v3, s[30:31]
	v_add_co_u32_e64 v200, s[30:31], s74, v2
	s_nop 1
	v_addc_co_u32_e64 v201, s[30:31], 0, v3, s[30:31]
	v_add_co_u32_e64 v204, s[30:31], s75, v2
	s_nop 1
	v_addc_co_u32_e64 v205, s[30:31], 0, v3, s[30:31]
	v_add_co_u32_e64 v208, s[30:31], s76, v2
	global_load_dwordx4 v[168:171], v[168:169], off
	s_nop 0
	global_load_dwordx4 v[172:175], v[172:173], off
	s_nop 0
	global_load_dwordx4 v[176:179], v[176:177], off
	s_nop 0
	global_load_dwordx4 v[180:183], v[180:181], off
	s_nop 0
	global_load_dwordx4 v[184:187], v[184:185], off
	s_nop 0
	global_load_dwordx4 v[188:191], v[188:189], off
	s_nop 0
	global_load_dwordx4 v[192:195], v[192:193], off
	s_nop 0
	global_load_dwordx4 v[196:199], v[196:197], off
	s_nop 0
	global_load_dwordx4 v[200:203], v[200:201], off
	s_nop 0
	global_load_dwordx4 v[204:207], v[204:205], off
	v_addc_co_u32_e64 v209, s[30:31], 0, v3, s[30:31]
	v_add_co_u32_e64 v212, s[30:31], s77, v2
	s_nop 0
	s_nop 0
	v_addc_co_u32_e64 v213, s[30:31], 0, v3, s[30:31]
	v_add_co_u32_e64 v216, s[30:31], s78, v2
	s_nop 0
	s_nop 0
	v_addc_co_u32_e64 v217, s[30:31], 0, v3, s[30:31]
	v_add_co_u32_e64 v6, s[30:31], s79, v2
	v_add_co_u32_e32 v2, vcc, 0x1b01000, v2
	s_nop 0
	v_addc_co_u32_e64 v7, s[30:31], 0, v3, s[30:31]
	global_load_dwordx4 v[208:211], v[208:209], off
	s_nop 0
	global_load_dwordx4 v[212:215], v[212:213], off
	s_nop 0
	global_load_dwordx4 v[216:219], v[216:217], off
	s_nop 0
	global_load_dwordx4 v[6:9], v[6:7], off
	v_addc_co_u32_e32 v3, vcc, 0, v3, vcc
	global_load_dwordx4 v[20:23], v[20:21], off
	s_nop 0
	global_load_dwordx2 v[24:25], v[2:3], off
	global_load_dwordx2 v[12:13], v[2:3], off offset:8
.LBB0_1335:
	s_waitcnt vmcnt(0) lgkmcnt(0)
	v_mov_b32_e32 v40, v168
	v_mov_b32_e32 v41, v169
	v_mov_b32_e32 v42, v170
	v_mov_b32_e32 v43, v171
	v_mov_b32_e32 v44, v172
	v_mov_b32_e32 v45, v173
	v_mov_b32_e32 v46, v174
	v_mov_b32_e32 v47, v175
	v_mov_b32_e32 v48, v176
	v_mov_b32_e32 v49, v177
	v_mov_b32_e32 v50, v178
	v_mov_b32_e32 v51, v179
	v_mov_b32_e32 v52, v180
	v_mov_b32_e32 v53, v181
	v_mov_b32_e32 v54, v182
	v_mov_b32_e32 v55, v183
	v_mov_b32_e32 v56, v184
	v_mov_b32_e32 v57, v185
	v_mov_b32_e32 v58, v186
	v_mov_b32_e32 v59, v187
	v_mov_b32_e32 v60, v188
	v_mov_b32_e32 v61, v189
	v_mov_b32_e32 v62, v190
	v_mov_b32_e32 v63, v191
	v_mov_b32_e32 v64, v192
	v_mov_b32_e32 v65, v193
	v_mov_b32_e32 v66, v194
	v_mov_b32_e32 v67, v195
	v_mov_b32_e32 v68, v196
	v_mov_b32_e32 v69, v197
	v_mov_b32_e32 v70, v198
	v_mov_b32_e32 v71, v199
	v_mov_b32_e32 v72, v200
	v_mov_b32_e32 v73, v201
	v_mov_b32_e32 v74, v202
	v_mov_b32_e32 v75, v203
	v_mov_b32_e32 v76, v204
	v_mov_b32_e32 v77, v205
	v_mov_b32_e32 v78, v206
	v_mov_b32_e32 v79, v207
	v_mov_b32_e32 v80, v208
	v_mov_b32_e32 v81, v209
	v_mov_b32_e32 v82, v210
	v_mov_b32_e32 v83, v211
	v_mov_b32_e32 v84, v212
	v_mov_b32_e32 v85, v213
	v_mov_b32_e32 v86, v214
	v_mov_b32_e32 v87, v215
	v_mov_b32_e32 v88, v216
	v_mov_b32_e32 v89, v217
	v_mov_b32_e32 v90, v218
	v_mov_b32_e32 v91, v219
	v_mov_b32_e32 v92, v6
	v_mov_b32_e32 v93, v7
	v_mov_b32_e32 v94, v8
	v_mov_b32_e32 v95, v9
	v_mov_b32_e32 v96, v20
	v_mov_b32_e32 v97, v21
	v_mov_b32_e32 v98, v22
	v_mov_b32_e32 v99, v23
	v_mov_b32_e32 v100, v24
	v_mov_b32_e32 v101, v25
	v_mov_b32_e32 v102, v12
	v_mov_b32_e32 v103, v13
	s_cmp_lg_u32 s54, 0x1c00000
	s_cbranch_scc0 .Lfq_skip
; __device__ __forceinline__ float bf2f(unsigned short h) { return __uint_as_float(((unsigned)h) << 16); }
; template <int CTRL> __device__ __forceinline__ float dppf(float old, float src) { return __builtin_bit_cast(float, __builtin_amdgcn_update_dpp(__builtin_bit_cast(int, old), __builtin_bit_cast(int, src), CTRL, 0xF, 0xF, false)); }
; __device__ __forceinline__ void p5a_fcum(const Args& A, char* lds, int G) {
;     ...
;         { const bf16* P1 = (const bf16*)(A.ws + WS_BIG); float qm = 0.f, km = 0.f;
; #pragma unroll 8
;           for (int i = 0; i < 32; ++i) { const size_t m = (size_t)b * SEQL + (tid >> 3) + 64 * i; const int c8 = tid & 7; float qs = 0.f, ks2 = 0.f;
;               const bf16x8 qv = *(const bf16x8*)(P1 + m * LD1 + C1_Q + h * 64 + c8 * 8), kv = *(const bf16x8*)(P1 + m * LD1 + C1_K + h * 64 + c8 * 8);
; #pragma unroll
;               for (int e = 0; e < 8; ++e) { const float qf = bf2f((unsigned short)qv[e]), kf = bf2f((unsigned short)kv[e]); qs += qf * qf; ks2 += kf * kf; }
;               qs += dppf<0xB1>(qs, qs); qs += dppf<0x4E>(qs, qs); qs += dppf<0x141>(qs, qs); ks2 += dppf<0xB1>(ks2, ks2); ks2 += dppf<0x4E>(ks2, ks2); ks2 += dppf<0x141>(ks2, ks2);
;               qm = fmaxf(qm, qs); km = fmaxf(km, ks2); }
	v_lshl_add_u64 v[2:3], v[0:1], 0, s[54:55]
	v_add_co_u32_e64 v168, s[30:31], s65, v2
	v_add_co_u32_e32 v20, vcc, 0x1b00000, v2
	s_nop 0
	v_addc_co_u32_e64 v169, s[30:31], 0, v3, s[30:31]
	v_add_co_u32_e64 v172, s[30:31], s66, v2
	v_addc_co_u32_e32 v21, vcc, 0, v3, vcc
	s_nop 0
	v_addc_co_u32_e64 v173, s[30:31], 0, v3, s[30:31]
	v_add_co_u32_e64 v176, s[30:31], s67, v2
	s_add_u32 s54, s54, 0x700000
	s_nop 0
	v_addc_co_u32_e64 v177, s[30:31], 0, v3, s[30:31]
	v_add_co_u32_e64 v180, s[30:31], s68, v2
	s_addc_u32 s55, s55, 0
	s_nop 0
	v_addc_co_u32_e64 v181, s[30:31], 0, v3, s[30:31]
	v_add_co_u32_e64 v184, s[30:31], s69, v2
	s_nop 0
	s_nop 0
	v_addc_co_u32_e64 v185, s[30:31], 0, v3, s[30:31]
	v_add_co_u32_e64 v188, s[30:31], s71, v2
	s_nop 1
	v_addc_co_u32_e64 v189, s[30:31], 0, v3, s[30:31]
	v_add_co_u32_e64 v192, s[30:31], s72, v2
	s_nop 1
	v_addc_co_u32_e64 v193, s[30:31], 0, v3, s[30:31]
	v_add_co_u32_e64 v196, s[30:31], s73, v2
	s_nop 1
	v_addc_co_u32_e64 v197, s[30:31], 0, v3, s[30:31]
	v_add_co_u32_e64 v200, s[30:31], s74, v2
	s_nop 1
	v_addc_co_u32_e64 v201, s[30:31], 0, v3, s[30:31]
	v_add_co_u32_e64 v204, s[30:31], s75, v2
	s_nop 1
	v_addc_co_u32_e64 v205, s[30:31], 0, v3, s[30:31]
	v_add_co_u32_e64 v208, s[30:31], s76, v2
	global_load_dwordx4 v[168:171], v[168:169], off
	s_nop 0
	global_load_dwordx4 v[172:175], v[172:173], off
	s_nop 0
	global_load_dwordx4 v[176:179], v[176:177], off
	s_nop 0
	global_load_dwordx4 v[180:183], v[180:181], off
	s_nop 0
	global_load_dwordx4 v[184:187], v[184:185], off
	s_nop 0
	global_load_dwordx4 v[188:191], v[188:189], off
	s_nop 0
	global_load_dwordx4 v[192:195], v[192:193], off
	s_nop 0
	global_load_dwordx4 v[196:199], v[196:197], off
	s_nop 0
	global_load_dwordx4 v[200:203], v[200:201], off
	s_nop 0
	global_load_dwordx4 v[204:207], v[204:205], off
	v_addc_co_u32_e64 v209, s[30:31], 0, v3, s[30:31]
	v_add_co_u32_e64 v212, s[30:31], s77, v2
	s_nop 0
	s_nop 0
	v_addc_co_u32_e64 v213, s[30:31], 0, v3, s[30:31]
	v_add_co_u32_e64 v216, s[30:31], s78, v2
	s_nop 0
	s_nop 0
	v_addc_co_u32_e64 v217, s[30:31], 0, v3, s[30:31]
	v_add_co_u32_e64 v6, s[30:31], s79, v2
	v_add_co_u32_e32 v2, vcc, 0x1b01000, v2
	s_nop 0
	v_addc_co_u32_e64 v7, s[30:31], 0, v3, s[30:31]
	global_load_dwordx4 v[208:211], v[208:209], off
	s_nop 0
	global_load_dwordx4 v[212:215], v[212:213], off
	s_nop 0
	global_load_dwordx4 v[216:219], v[216:217], off
	s_nop 0
	global_load_dwordx4 v[6:9], v[6:7], off
	v_addc_co_u32_e32 v3, vcc, 0, v3, vcc
	global_load_dwordx4 v[20:23], v[20:21], off
	s_nop 0
	global_load_dwordx2 v[24:25], v[2:3], off
	global_load_dwordx2 v[12:13], v[2:3], off offset:8
	s_cmp_eq_u32 s54, s54
.Lfq_skip:
	v_and_b32_e32 v107, 0xffff0000, v41
	v_and_b32_e32 v105, 0xffff0000, v44
	v_and_b32_e32 v3, 0xffff0000, v40
	v_lshlrev_b32_e32 v2, 16, v40
	v_lshlrev_b32_e32 v104, 16, v44
	v_lshlrev_b32_e32 v106, 16, v41
	v_and_b32_e32 v109, 0xffff0000, v46
	v_lshlrev_b32_e32 v108, 16, v46
	v_and_b32_e32 v111, 0xffff0000, v43
	v_lshlrev_b32_e32 v110, 16, v43
	v_and_b32_e32 v113, 0xffff0000, v52
	v_lshlrev_b32_e32 v112, 16, v52
	v_and_b32_e32 v115, 0xffff0000, v49
	v_lshlrev_b32_e32 v114, 16, v49
	v_and_b32_e32 v117, 0xffff0000, v54
	v_lshlrev_b32_e32 v116, 16, v54
	v_and_b32_e32 v119, 0xffff0000, v51
	v_lshlrev_b32_e32 v118, 16, v51
	v_and_b32_e32 v121, 0xffff0000, v60
	v_lshlrev_b32_e32 v120, 16, v60
	v_and_b32_e32 v123, 0xffff0000, v57
	v_lshlrev_b32_e32 v122, 16, v57
	v_and_b32_e32 v125, 0xffff0000, v62
	v_lshlrev_b32_e32 v124, 16, v62
	v_and_b32_e32 v127, 0xffff0000, v59
	v_lshlrev_b32_e32 v126, 16, v59
	v_and_b32_e32 v129, 0xffff0000, v68
	v_lshlrev_b32_e32 v128, 16, v68
	v_and_b32_e32 v131, 0xffff0000, v65
	v_lshlrev_b32_e32 v130, 16, v65
	v_and_b32_e32 v133, 0xffff0000, v70
	v_lshlrev_b32_e32 v132, 16, v70
	v_and_b32_e32 v135, 0xffff0000, v67
	v_lshlrev_b32_e32 v134, 16, v67
	v_and_b32_e32 v137, 0xffff0000, v76
	v_lshlrev_b32_e32 v136, 16, v76
	v_and_b32_e32 v139, 0xffff0000, v73
	v_lshlrev_b32_e32 v138, 16, v73
	v_and_b32_e32 v141, 0xffff0000, v78
	v_lshlrev_b32_e32 v140, 16, v78
	v_and_b32_e32 v143, 0xffff0000, v75
	v_lshlrev_b32_e32 v142, 16, v75
	v_and_b32_e32 v41, 0xffff0000, v45
	v_lshlrev_b32_e32 v40, 16, v45
	v_and_b32_e32 v45, 0xffff0000, v42
	v_lshlrev_b32_e32 v44, 16, v42
	v_and_b32_e32 v43, 0xffff0000, v47
	v_lshlrev_b32_e32 v42, 16, v47
	v_and_b32_e32 v47, 0xffff0000, v48
	v_lshlrev_b32_e32 v46, 16, v48
	v_and_b32_e32 v49, 0xffff0000, v53
	v_lshlrev_b32_e32 v48, 16, v53
	v_and_b32_e32 v53, 0xffff0000, v50
	v_lshlrev_b32_e32 v52, 16, v50
	v_and_b32_e32 v51, 0xffff0000, v55
	v_lshlrev_b32_e32 v50, 16, v55
	v_and_b32_e32 v55, 0xffff0000, v56
	v_lshlrev_b32_e32 v54, 16, v56
	v_and_b32_e32 v57, 0xffff0000, v61
	v_lshlrev_b32_e32 v56, 16, v61
	v_and_b32_e32 v61, 0xffff0000, v58
	v_lshlrev_b32_e32 v60, 16, v58
	v_and_b32_e32 v59, 0xffff0000, v63
	v_lshlrev_b32_e32 v58, 16, v63
	v_and_b32_e32 v63, 0xffff0000, v64
	v_lshlrev_b32_e32 v62, 16, v64
	v_and_b32_e32 v65, 0xffff0000, v69
	v_lshlrev_b32_e32 v64, 16, v69
	v_and_b32_e32 v69, 0xffff0000, v66
	v_lshlrev_b32_e32 v68, 16, v66
	v_and_b32_e32 v67, 0xffff0000, v71
	v_lshlrev_b32_e32 v66, 16, v71
	v_and_b32_e32 v71, 0xffff0000, v72
	v_lshlrev_b32_e32 v70, 16, v72
	v_and_b32_e32 v73, 0xffff0000, v77
	v_and_b32_e32 v147, 0xffff0000, v81
	v_and_b32_e32 v145, 0xffff0000, v84
	v_lshlrev_b32_e32 v144, 16, v84
	v_lshlrev_b32_e32 v146, 16, v81
	v_and_b32_e32 v149, 0xffff0000, v86
	v_lshlrev_b32_e32 v148, 16, v86
	v_and_b32_e32 v151, 0xffff0000, v83
	v_lshlrev_b32_e32 v150, 16, v83
	v_and_b32_e32 v153, 0xffff0000, v92
	v_lshlrev_b32_e32 v152, 16, v92
	v_and_b32_e32 v155, 0xffff0000, v89
; __device__ __forceinline__ float bf2f(unsigned short h) { return __uint_as_float(((unsigned)h) << 16); }
; __device__ __forceinline__ void p5a_fcum(const Args& A, char* lds, int G) {
;     ...
; #pragma unroll
;               for (int e = 0; e < 8; ++e) { const float qf = bf2f((unsigned short)qv[e]), kf = bf2f((unsigned short)kv[e]); qs += qf * qf; ks2 += kf * kf; }
	v_lshlrev_b32_e32 v154, 16, v89
	v_and_b32_e32 v157, 0xffff0000, v94
	v_lshlrev_b32_e32 v156, 16, v94
	v_and_b32_e32 v159, 0xffff0000, v91
	v_lshlrev_b32_e32 v158, 16, v91
	v_lshlrev_b32_e32 v72, 16, v77
	v_and_b32_e32 v77, 0xffff0000, v74
	v_lshlrev_b32_e32 v76, 16, v74
	v_and_b32_e32 v75, 0xffff0000, v79
	v_lshlrev_b32_e32 v74, 16, v79
	v_and_b32_e32 v79, 0xffff0000, v80
	v_lshlrev_b32_e32 v78, 16, v80
	v_and_b32_e32 v81, 0xffff0000, v85
	v_lshlrev_b32_e32 v80, 16, v85
	v_and_b32_e32 v85, 0xffff0000, v82
	v_lshlrev_b32_e32 v84, 16, v82
	v_and_b32_e32 v83, 0xffff0000, v87
	v_lshlrev_b32_e32 v82, 16, v87
	v_and_b32_e32 v87, 0xffff0000, v88
	v_lshlrev_b32_e32 v86, 16, v88
	v_and_b32_e32 v89, 0xffff0000, v93
	v_lshlrev_b32_e32 v88, 16, v93
	v_and_b32_e32 v93, 0xffff0000, v90
	v_lshlrev_b32_e32 v92, 16, v90
	v_and_b32_e32 v91, 0xffff0000, v95
	v_lshlrev_b32_e32 v90, 16, v95
	v_and_b32_e32 v95, 0xffff0000, v96
	v_lshlrev_b32_e32 v94, 16, v96
	v_and_b32_e32 v161, 0xffff0000, v97
	v_lshlrev_b32_e32 v160, 16, v97
	v_and_b32_e32 v97, 0xffff0000, v98
	v_lshlrev_b32_e32 v96, 16, v98
	v_and_b32_e32 v163, 0xffff0000, v99
	v_lshlrev_b32_e32 v162, 16, v99
	v_pk_mul_f32 v[2:3], v[2:3], v[2:3]
	v_pk_mul_f32 v[98:99], v[104:105], v[104:105]
	v_pk_mul_f32 v[104:105], v[106:107], v[106:107]
	v_pk_mul_f32 v[106:107], v[108:109], v[108:109]
	v_pk_mul_f32 v[108:109], v[110:111], v[110:111]
	v_pk_mul_f32 v[110:111], v[112:113], v[112:113]
	v_pk_mul_f32 v[112:113], v[114:115], v[114:115]
	v_pk_mul_f32 v[114:115], v[116:117], v[116:117]
	v_pk_mul_f32 v[116:117], v[118:119], v[118:119]
	v_pk_mul_f32 v[118:119], v[120:121], v[120:121]
	v_pk_mul_f32 v[120:121], v[122:123], v[122:123]
	v_pk_mul_f32 v[122:123], v[124:125], v[124:125]
	v_pk_mul_f32 v[124:125], v[126:127], v[126:127]
	v_pk_mul_f32 v[126:127], v[128:129], v[128:129]
	v_pk_mul_f32 v[128:129], v[130:131], v[130:131]
	v_pk_mul_f32 v[130:131], v[132:133], v[132:133]
	v_pk_mul_f32 v[132:133], v[134:135], v[134:135]
	v_pk_mul_f32 v[134:135], v[136:137], v[136:137]
	v_pk_mul_f32 v[136:137], v[138:139], v[138:139]
	v_pk_mul_f32 v[138:139], v[140:141], v[140:141]
	v_pk_mul_f32 v[140:141], v[142:143], v[142:143]
	v_pk_mul_f32 v[142:143], v[144:145], v[144:145]
	v_pk_mul_f32 v[144:145], v[146:147], v[146:147]
	v_pk_mul_f32 v[146:147], v[148:149], v[148:149]
	v_pk_mul_f32 v[148:149], v[150:151], v[150:151]
	v_pk_mul_f32 v[150:151], v[152:153], v[152:153]
	v_pk_mul_f32 v[152:153], v[154:155], v[154:155]
	v_pk_mul_f32 v[154:155], v[156:157], v[156:157]
	v_pk_mul_f32 v[156:157], v[158:159], v[158:159]
	v_and_b32_e32 v159, 0xffff0000, v100
	v_lshlrev_b32_e32 v158, 16, v100
	v_pk_mul_f32 v[46:47], v[46:47], v[46:47]
	v_pk_mul_f32 v[54:55], v[54:55], v[54:55]
	v_pk_mul_f32 v[62:63], v[62:63], v[62:63]
	v_pk_mul_f32 v[70:71], v[70:71], v[70:71]
	v_pk_mul_f32 v[78:79], v[78:79], v[78:79]
	v_pk_mul_f32 v[86:87], v[86:87], v[86:87]
	v_pk_mul_f32 v[94:95], v[94:95], v[94:95]
	v_and_b32_e32 v165, 0xffff0000, v101
	v_lshlrev_b32_e32 v164, 16, v101
	v_add_f32_e32 v15, v2, v3
	v_pk_mul_f32 v[2:3], v[158:159], v[158:159]
	v_pk_mul_f32 v[40:41], v[40:41], v[40:41]
	v_pk_mul_f32 v[48:49], v[48:49], v[48:49]
	v_pk_mul_f32 v[56:57], v[56:57], v[56:57]
	v_pk_mul_f32 v[64:65], v[64:65], v[64:65]
	v_pk_mul_f32 v[72:73], v[72:73], v[72:73]
	v_pk_mul_f32 v[80:81], v[80:81], v[80:81]
	v_pk_mul_f32 v[160:161], v[160:161], v[160:161]
	v_and_b32_e32 v101, 0xffff0000, v102
	v_lshlrev_b32_e32 v100, 16, v102
	v_and_b32_e32 v167, 0xffff0000, v103
	v_lshlrev_b32_e32 v166, 16, v103
	v_add_f32_e32 v39, v98, v99
	v_add_f32_e32 v98, v46, v47
	v_add_f32_e32 v99, v110, v111
	v_add_f32_e32 v102, v54, v55
	v_add_f32_e32 v103, v118, v119
	v_add_f32_e32 v110, v62, v63
	v_add_f32_e32 v111, v126, v127
	v_add_f32_e32 v70, v70, v71
	v_add_f32_e32 v71, v134, v135
	v_add_f32_e32 v78, v78, v79
	v_add_f32_e32 v79, v142, v143
	v_add_f32_e32 v86, v86, v87
	v_pk_mul_f32 v[46:47], v[164:165], v[164:165]
	v_add_f32_e32 v94, v94, v95
	v_add_f32_e32 v2, v2, v3
	v_pk_mul_f32 v[88:89], v[88:89], v[88:89]
	v_add_f32_e32 v87, v150, v151
	v_add_f32_e32 v15, v104, v15
	v_add_f32_e32 v39, v40, v39
	v_add_f32_e32 v40, v112, v98
	v_add_f32_e32 v48, v48, v99
	v_add_f32_e32 v95, v120, v102
	v_add_f32_e32 v56, v56, v103
	v_add_f32_e32 v98, v128, v110
	v_add_f32_e32 v64, v64, v111
	v_add_f32_e32 v70, v136, v70
	v_add_f32_e32 v71, v72, v71
	v_add_f32_e32 v72, v144, v78
	v_add_f32_e32 v78, v80, v79
	v_add_f32_e32 v79, v152, v86
	v_add_f32_e32 v86, v160, v94
	v_add_f32_e32 v2, v46, v2
	v_pk_mul_f32 v[44:45], v[44:45], v[44:45]
	v_pk_mul_f32 v[52:53], v[52:53], v[52:53]
	v_pk_mul_f32 v[60:61], v[60:61], v[60:61]
	v_pk_mul_f32 v[68:69], v[68:69], v[68:69]
	v_pk_mul_f32 v[76:77], v[76:77], v[76:77]
	v_pk_mul_f32 v[84:85], v[84:85], v[84:85]
	v_pk_mul_f32 v[92:93], v[92:93], v[92:93]
	v_pk_mul_f32 v[96:97], v[96:97], v[96:97]
	v_pk_mul_f32 v[54:55], v[100:101], v[100:101]
	v_add_f32_e32 v80, v88, v87
	v_add_f32_e32 v3, v105, v15
	v_add_f32_e32 v15, v41, v39
	v_add_f32_e32 v39, v113, v40
	v_add_f32_e32 v40, v49, v48
	v_add_f32_e32 v41, v121, v95
	v_add_f32_e32 v48, v57, v56
	v_add_f32_e32 v49, v129, v98
	v_add_f32_e32 v56, v65, v64
	v_add_f32_e32 v57, v137, v70
	v_add_f32_e32 v64, v73, v71
	v_add_f32_e32 v65, v145, v72
	v_add_f32_e32 v70, v81, v78
	v_add_f32_e32 v71, v153, v79
	v_add_f32_e32 v73, v161, v86
	v_add_f32_e32 v2, v47, v2
	v_add_f32_e32 v72, v89, v80
	v_add_f32_e32 v3, v44, v3
	v_add_f32_e32 v15, v106, v15
	v_add_f32_e32 v39, v52, v39
	v_add_f32_e32 v40, v114, v40
	v_add_f32_e32 v41, v60, v41
	v_add_f32_e32 v44, v122, v48
	v_add_f32_e32 v46, v68, v49
	v_add_f32_e32 v48, v130, v56
; __device__ __forceinline__ float bf2f(unsigned short h) { return __uint_as_float(((unsigned)h) << 16); }
; template <int CTRL> __device__ __forceinline__ float dppf(float old, float src) { return __builtin_bit_cast(float, __builtin_amdgcn_update_dpp(__builtin_bit_cast(int, old), __builtin_bit_cast(int, src), CTRL, 0xF, 0xF, false)); }
; __device__ __forceinline__ void p5a_fcum(const Args& A, char* lds, int G) {
;     ...
;               for (int e = 0; e < 8; ++e) { const float qf = bf2f((unsigned short)qv[e]), kf = bf2f((unsigned short)kv[e]); qs += qf * qf; ks2 += kf * kf; }
;               qs += dppf<0xB1>(qs, qs); qs += dppf<0x4E>(qs, qs); qs += dppf<0x141>(qs, qs); ks2 += dppf<0xB1>(ks2, ks2); ks2 += dppf<0x4E>(ks2, ks2); ks2 += dppf<0x141>(ks2, ks2);
	v_add_f32_e32 v49, v76, v57
	v_add_f32_e32 v52, v138, v64
	v_add_f32_e32 v56, v84, v65
	v_add_f32_e32 v57, v146, v70
	v_add_f32_e32 v60, v92, v71
	v_add_f32_e32 v65, v96, v73
	v_add_f32_e32 v2, v54, v2
	v_pk_mul_f32 v[42:43], v[42:43], v[42:43]
	v_pk_mul_f32 v[50:51], v[50:51], v[50:51]
	v_pk_mul_f32 v[162:163], v[162:163], v[162:163]
	v_pk_mul_f32 v[62:63], v[166:167], v[166:167]
	v_add_f32_e32 v64, v154, v72
	v_add_f32_e32 v3, v45, v3
	v_add_f32_e32 v15, v107, v15
	v_add_f32_e32 v39, v53, v39
	v_add_f32_e32 v40, v115, v40
	v_add_f32_e32 v45, v69, v46
	v_add_f32_e32 v46, v131, v48
	v_add_f32_e32 v48, v139, v52
	v_add_f32_e32 v52, v147, v57
	v_add_f32_e32 v53, v93, v60
	v_add_f32_e32 v57, v97, v65
	v_add_f32_e32 v2, v55, v2
	v_pk_mul_f32 v[58:59], v[58:59], v[58:59]
	v_pk_mul_f32 v[66:67], v[66:67], v[66:67]
	v_pk_mul_f32 v[74:75], v[74:75], v[74:75]
	v_pk_mul_f32 v[82:83], v[82:83], v[82:83]
	v_pk_mul_f32 v[90:91], v[90:91], v[90:91]
	v_add_f32_e32 v41, v61, v41
	v_add_f32_e32 v44, v123, v44
	v_add_f32_e32 v47, v77, v49
	v_add_f32_e32 v49, v85, v56
	v_add_f32_e32 v56, v155, v64
	v_add_f32_e32 v3, v108, v3
	v_add_f32_e32 v15, v42, v15
	v_add_f32_e32 v40, v50, v40
	v_add_f32_e32 v50, v156, v53
	v_add_f32_e32 v53, v162, v57
	v_add_f32_e32 v2, v62, v2
	v_add_f32_e32 v39, v116, v39
	v_add_f32_e32 v41, v124, v41
	v_add_f32_e32 v42, v58, v44
	v_add_f32_e32 v44, v132, v45
	v_add_f32_e32 v45, v66, v46
	v_add_f32_e32 v46, v140, v47
	v_add_f32_e32 v47, v74, v48
	v_add_f32_e32 v48, v148, v49
	v_add_f32_e32 v49, v82, v52
	v_add_f32_e32 v52, v90, v56
	v_add_f32_e32 v3, v109, v3
	v_add_f32_e32 v15, v43, v15
	v_add_f32_e32 v40, v51, v40
	v_add_f32_e32 v51, v163, v53
	v_add_f32_e32 v2, v63, v2
	v_add_f32_e32 v39, v117, v39
	v_add_f32_e32 v41, v125, v41
	v_add_f32_e32 v42, v59, v42
	v_add_f32_e32 v43, v133, v44
	v_add_f32_e32 v44, v67, v45
	v_add_f32_e32 v45, v141, v46
	v_add_f32_e32 v46, v75, v47
	v_add_f32_e32 v47, v149, v48
	v_add_f32_e32 v48, v83, v49
	v_add_f32_e32 v49, v157, v50
	v_add_f32_e32 v50, v91, v52
	v_mov_b32_e32 v52, v3
	v_mov_b32_e32 v53, v15
	v_mov_b32_e32 v63, v51
	v_mov_b32_e32 v67, v2
	v_mov_b32_e32 v54, v39
	v_mov_b32_e32 v55, v40
	v_mov_b32_e32 v56, v41
	v_mov_b32_e32 v57, v42
	v_mov_b32_e32 v66, v50
	v_mov_b32_dpp v52, v52 quad_perm:[1,0,3,2] row_mask:0xf bank_mask:0xf
	v_mov_b32_dpp v53, v53 quad_perm:[1,0,3,2] row_mask:0xf bank_mask:0xf
	v_mov_b32_dpp v63, v63 quad_perm:[1,0,3,2] row_mask:0xf bank_mask:0xf
	v_mov_b32_dpp v67, v67 quad_perm:[1,0,3,2] row_mask:0xf bank_mask:0xf
	v_mov_b32_e32 v58, v43
	v_mov_b32_e32 v59, v44
	v_mov_b32_e32 v60, v45
	v_mov_b32_e32 v61, v46
	v_mov_b32_dpp v54, v54 quad_perm:[1,0,3,2] row_mask:0xf bank_mask:0xf
	v_mov_b32_dpp v55, v55 quad_perm:[1,0,3,2] row_mask:0xf bank_mask:0xf
	v_mov_b32_dpp v56, v56 quad_perm:[1,0,3,2] row_mask:0xf bank_mask:0xf
	v_mov_b32_dpp v57, v57 quad_perm:[1,0,3,2] row_mask:0xf bank_mask:0xf
	v_mov_b32_dpp v66, v66 quad_perm:[1,0,3,2] row_mask:0xf bank_mask:0xf
	v_add_f32_e32 v3, v3, v52
	v_add_f32_e32 v15, v15, v53
	v_add_f32_e32 v51, v51, v63
	v_add_f32_e32 v2, v2, v67
	v_mov_b32_e32 v62, v47
	v_mov_b32_e32 v64, v48
	v_mov_b32_e32 v65, v49
	v_mov_b32_dpp v58, v58 quad_perm:[1,0,3,2] row_mask:0xf bank_mask:0xf
	v_mov_b32_dpp v59, v59 quad_perm:[1,0,3,2] row_mask:0xf bank_mask:0xf
	v_mov_b32_dpp v60, v60 quad_perm:[1,0,3,2] row_mask:0xf bank_mask:0xf
	v_mov_b32_dpp v61, v61 quad_perm:[1,0,3,2] row_mask:0xf bank_mask:0xf
	v_add_f32_e32 v39, v39, v54
	v_add_f32_e32 v40, v40, v55
	v_add_f32_e32 v41, v41, v56
	v_add_f32_e32 v42, v42, v57
	v_add_f32_e32 v50, v50, v66
	v_mov_b32_e32 v52, v3
	v_mov_b32_e32 v53, v15
	v_mov_b32_e32 v66, v51
	v_mov_b32_e32 v67, v2
	v_mov_b32_dpp v62, v62 quad_perm:[1,0,3,2] row_mask:0xf bank_mask:0xf
	v_mov_b32_dpp v64, v64 quad_perm:[1,0,3,2] row_mask:0xf bank_mask:0xf
	v_mov_b32_dpp v65, v65 quad_perm:[1,0,3,2] row_mask:0xf bank_mask:0xf
	v_add_f32_e32 v43, v43, v58
	v_add_f32_e32 v44, v44, v59
	v_add_f32_e32 v45, v45, v60
	v_add_f32_e32 v46, v46, v61
	v_mov_b32_e32 v54, v39
	v_mov_b32_e32 v55, v40
	v_mov_b32_e32 v56, v41
	v_mov_b32_e32 v57, v42
	v_mov_b32_dpp v52, v52 quad_perm:[2,3,0,1] row_mask:0xf bank_mask:0xf
	v_mov_b32_dpp v53, v53 quad_perm:[2,3,0,1] row_mask:0xf bank_mask:0xf
	v_mov_b32_dpp v66, v66 quad_perm:[2,3,0,1] row_mask:0xf bank_mask:0xf
	v_mov_b32_dpp v67, v67 quad_perm:[2,3,0,1] row_mask:0xf bank_mask:0xf
	v_add_f32_e32 v47, v47, v62
	v_add_f32_e32 v48, v48, v64
	v_add_f32_e32 v49, v49, v65
	v_mov_b32_e32 v58, v43
	v_mov_b32_e32 v59, v44
	v_mov_b32_e32 v60, v45
	v_mov_b32_e32 v61, v46
	v_mov_b32_dpp v54, v54 quad_perm:[2,3,0,1] row_mask:0xf bank_mask:0xf
	v_mov_b32_dpp v55, v55 quad_perm:[2,3,0,1] row_mask:0xf bank_mask:0xf
	v_mov_b32_dpp v56, v56 quad_perm:[2,3,0,1] row_mask:0xf bank_mask:0xf
; template <int CTRL> __device__ __forceinline__ float dppf(float old, float src) { return __builtin_bit_cast(float, __builtin_amdgcn_update_dpp(__builtin_bit_cast(int, old), __builtin_bit_cast(int, src), CTRL, 0xF, 0xF, false)); }
; __device__ __forceinline__ void p5a_fcum(const Args& A, char* lds, int G) {
;     ...
;               qs += dppf<0xB1>(qs, qs); qs += dppf<0x4E>(qs, qs); qs += dppf<0x141>(qs, qs); ks2 += dppf<0xB1>(ks2, ks2); ks2 += dppf<0x4E>(ks2, ks2); ks2 += dppf<0x141>(ks2, ks2);
;               qm = fmaxf(qm, qs); km = fmaxf(km, ks2); }
; #pragma unroll
;           for (int o = 1; o < 64; o <<= 1) { qm = fmaxf(qm, __shfl_xor(qm, o)); km = fmaxf(km, __shfl_xor(km, o)); }
;           __syncthreads();
;           if (lane == 0) { wtot[16 + wave] = qm; wtot[32 + wave] = km; }
;           __syncthreads();
;           if (tid < 8) { float a = 0.f, c = 0.f; for (int w = 0; w < 8; ++w) { a = fmaxf(a, wtot[16 + w]); c = fmaxf(c, wtot[32 + w]); } const float u2 = 2.f * sqrtf(a) * sqrtf(c) * 1.01f;
	v_mov_b32_dpp v57, v57 quad_perm:[2,3,0,1] row_mask:0xf bank_mask:0xf
	v_add_f32_e32 v3, v3, v52
	v_add_f32_e32 v15, v15, v53
	v_add_f32_e32 v51, v51, v66
	v_add_f32_e32 v2, v2, v67
	v_mov_b32_e32 v62, v47
	v_mov_b32_e32 v63, v48
	v_mov_b32_e32 v64, v49
	v_mov_b32_e32 v65, v50
	v_mov_b32_dpp v58, v58 quad_perm:[2,3,0,1] row_mask:0xf bank_mask:0xf
	v_mov_b32_dpp v59, v59 quad_perm:[2,3,0,1] row_mask:0xf bank_mask:0xf
	v_mov_b32_dpp v60, v60 quad_perm:[2,3,0,1] row_mask:0xf bank_mask:0xf
	v_mov_b32_dpp v61, v61 quad_perm:[2,3,0,1] row_mask:0xf bank_mask:0xf
	v_add_f32_e32 v39, v39, v54
	v_add_f32_e32 v40, v40, v55
	v_add_f32_e32 v41, v41, v56
	v_add_f32_e32 v42, v42, v57
	v_mov_b32_e32 v52, v3
	v_mov_b32_e32 v53, v15
	v_mov_b32_e32 v66, v51
	v_mov_b32_e32 v67, v2
	v_mov_b32_dpp v62, v62 quad_perm:[2,3,0,1] row_mask:0xf bank_mask:0xf
	v_mov_b32_dpp v63, v63 quad_perm:[2,3,0,1] row_mask:0xf bank_mask:0xf
	v_mov_b32_dpp v64, v64 quad_perm:[2,3,0,1] row_mask:0xf bank_mask:0xf
	v_mov_b32_dpp v65, v65 quad_perm:[2,3,0,1] row_mask:0xf bank_mask:0xf
	v_add_f32_e32 v43, v43, v58
	v_add_f32_e32 v44, v44, v59
	v_add_f32_e32 v45, v45, v60
	v_add_f32_e32 v46, v46, v61
	v_mov_b32_e32 v54, v39
	v_mov_b32_e32 v55, v40
	v_mov_b32_e32 v56, v41
	v_mov_b32_e32 v57, v42
	v_mov_b32_dpp v52, v52 row_half_mirror row_mask:0xf bank_mask:0xf
	v_mov_b32_dpp v53, v53 row_half_mirror row_mask:0xf bank_mask:0xf
	v_mov_b32_dpp v66, v66 row_half_mirror row_mask:0xf bank_mask:0xf
	v_mov_b32_dpp v67, v67 row_half_mirror row_mask:0xf bank_mask:0xf
	v_add_f32_e32 v47, v47, v62
	v_add_f32_e32 v48, v48, v63
	v_add_f32_e32 v49, v49, v64
	v_add_f32_e32 v50, v50, v65
	v_mov_b32_e32 v58, v43
	v_mov_b32_e32 v59, v44
	v_mov_b32_e32 v60, v45
	v_mov_b32_e32 v61, v46
	v_mov_b32_dpp v54, v54 row_half_mirror row_mask:0xf bank_mask:0xf
	v_mov_b32_dpp v55, v55 row_half_mirror row_mask:0xf bank_mask:0xf
	v_mov_b32_dpp v56, v56 row_half_mirror row_mask:0xf bank_mask:0xf
	v_mov_b32_dpp v57, v57 row_half_mirror row_mask:0xf bank_mask:0xf
	v_add_f32_e32 v3, v3, v52
	v_add_f32_e32 v15, v15, v53
	v_add_f32_e32 v51, v51, v66
	v_add_f32_e32 v2, v2, v67
	v_mov_b32_e32 v62, v47
	v_mov_b32_e32 v63, v48
	v_mov_b32_e32 v64, v49
	v_mov_b32_e32 v65, v50
	v_mov_b32_dpp v58, v58 row_half_mirror row_mask:0xf bank_mask:0xf
	v_mov_b32_dpp v59, v59 row_half_mirror row_mask:0xf bank_mask:0xf
	v_mov_b32_dpp v60, v60 row_half_mirror row_mask:0xf bank_mask:0xf
	v_mov_b32_dpp v61, v61 row_half_mirror row_mask:0xf bank_mask:0xf
	v_add_f32_e32 v39, v39, v54
	v_add_f32_e32 v40, v40, v55
	v_add_f32_e32 v41, v41, v56
	v_add_f32_e32 v42, v42, v57
	v_max3_f32 v3, v14, v51, v3
	v_max3_f32 v2, v11, v2, v15
	v_mov_b32_dpp v62, v62 row_half_mirror row_mask:0xf bank_mask:0xf
	v_mov_b32_dpp v63, v63 row_half_mirror row_mask:0xf bank_mask:0xf
	v_mov_b32_dpp v64, v64 row_half_mirror row_mask:0xf bank_mask:0xf
	v_mov_b32_dpp v65, v65 row_half_mirror row_mask:0xf bank_mask:0xf
	v_add_f32_e32 v43, v43, v58
	v_add_f32_e32 v44, v44, v59
	v_add_f32_e32 v45, v45, v60
	v_add_f32_e32 v46, v46, v61
	v_max3_f32 v3, v3, v39, v41
	v_max3_f32 v2, v2, v40, v42
	v_add_f32_e32 v47, v47, v62
	v_add_f32_e32 v48, v48, v63
	v_add_f32_e32 v49, v49, v64
	v_add_f32_e32 v50, v50, v65
	v_max3_f32 v3, v3, v43, v45
	v_max3_f32 v2, v2, v44, v46
	v_max3_f32 v14, v3, v47, v49
	v_max3_f32 v11, v2, v48, v50
	s_cbranch_scc1 .LBB0_1335
	ds_bpermute_b32 v0, v26, v14
	ds_bpermute_b32 v1, v26, v11
	v_max_f32_e32 v2, v14, v14
	v_max_f32_e32 v3, v11, v11
	s_waitcnt lgkmcnt(0)
	v_max_f32_e32 v0, v0, v0
	v_max_f32_e32 v1, v1, v1
	v_max_f32_e32 v0, v2, v0
	v_max_f32_e32 v1, v3, v1
	ds_bpermute_b32 v2, v27, v0
	ds_bpermute_b32 v3, v27, v1
	s_barrier
	s_waitcnt lgkmcnt(0)
	v_max_f32_e32 v2, v2, v2
	v_max_f32_e32 v3, v3, v3
	v_max_f32_e32 v0, v0, v2
	v_max_f32_e32 v1, v1, v3
	ds_bpermute_b32 v2, v28, v0
	ds_bpermute_b32 v3, v28, v1
	s_waitcnt lgkmcnt(1)
	v_max_f32_e32 v2, v2, v2
	s_waitcnt lgkmcnt(0)
	v_max_f32_e32 v3, v3, v3
	v_max_f32_e32 v0, v0, v2
	v_max_f32_e32 v1, v1, v3
	ds_bpermute_b32 v2, v29, v0
	ds_bpermute_b32 v3, v29, v1
	s_waitcnt lgkmcnt(1)
	v_max_f32_e32 v2, v2, v2
	s_waitcnt lgkmcnt(0)
	v_max_f32_e32 v3, v3, v3
	v_max_f32_e32 v0, v0, v2
	v_max_f32_e32 v2, v1, v3
	ds_bpermute_b32 v1, v30, v0
	ds_bpermute_b32 v3, v30, v2
	s_waitcnt lgkmcnt(1)
	v_max_f32_e32 v1, v1, v1
	s_waitcnt lgkmcnt(0)
	v_max_f32_e32 v3, v3, v3
	v_max_f32_e32 v1, v0, v1
	v_max_f32_e32 v0, v2, v3
	ds_bpermute_b32 v3, v31, v1
	ds_bpermute_b32 v2, v31, v0
	s_and_saveexec_b64 s[30:31], s[10:11]
	s_cbranch_execz .LBB0_1338
	s_waitcnt lgkmcnt(1)
	v_max_f32_e32 v3, v3, v3
	v_max_f32_e32 v1, v1, v1
	s_waitcnt lgkmcnt(0)
	v_max_f32_e32 v2, v2, v2
	v_max_f32_e32 v0, v0, v0
	v_max_f32_e32 v1, v1, v3
	v_max_f32_e32 v0, v0, v2
	ds_write2_b32 v17, v1, v0 offset0:16 offset1:32
